# v32
# speedup vs baseline: 1.0027x; 1.0027x over previous
; DEVI f32x4 mfma(bf16x8 a, bf16x8 b, f32x4 c) { return __builtin_amdgcn_mfma_f32_16x16x32_bf16(a, b, c, 0, 0, 0); }
; DEVI void attn_unit(const Params& p, char* lds, int au) {
;     ...
;     const float sgn = (kt < ktw) ? 1.f : ((kt > ktw) ? -1.f : 0.f);
;     f32x4 sc[4][2];
;     float rc[2];
;     rc[0] = sgn * slope2 * ((float)(kt * 64) - qpos[0]);
;     rc[1] = sgn * slope2 * ((float)(kt * 64) - qpos[1]);
;     {
;       bf16x8 kf[4][2];
; #pragma unroll
;       for (int kb = 0; kb < 4; ++kb)
; #pragma unroll
;         for (int kk = 0; kk < 2; ++kk)
;           kf[kb][kk] = *(const bf16x8*)(Ks + (kb * 16 + fr) * 256 + (((mp * 8 + kk * 4 + fq) ^ fr) << 4));
;       const float ss2 = sgn * slope2;
;       const float b0 = sgn * cl0 + rc[0] - mrun[0], b1 = sgn * cl0 + rc[1] - mrun[1];
; #pragma unroll
;       for (int kb = 0; kb < 4; ++kb)
; #pragma unroll
;         for (int j = 0; j < 4; ++j) {
;           sc[kb][0][j] = b0 + ss2 * (float)(kb * 16 + j);
;           sc[kb][1][j] = b1 + ss2 * (float)(kb * 16 + j);
;         }
;       __builtin_amdgcn_sched_barrier(0);
; #pragma unroll
;       for (int kk = 0; kk < 2; ++kk)
; #pragma unroll
;         for (int kb = 0; kb < 4; ++kb) {
;           sc[kb][0] = mfma(kf[kb][kk], qf[0][kk], sc[kb][0]);
;           sc[kb][1] = mfma(kf[kb][kk], qf[1][kk], sc[kb][1]);
;         }
.LBB0_210:
	s_add_i32 s3, s18, -1
	s_add_i32 s18, s8, 1
	s_add_i32 s2, s2, 2
	s_cmp_gt_i32 s3, s6
	s_cselect_b32 s20, s2, s18
	s_lshl_b32 s18, s20, 6
	v_cvt_f32_i32_e32 v90, s18
	v_cmp_gt_i32_e32 vcc, s20, v0
	v_sub_f32_e32 v119, v90, v62
	v_sub_f32_e32 v120, v90, v64
	v_add_u32_e32 v90, s19, v180
	v_add_u32_e32 v110, v90, v181
	v_add_u32_e32 v121, v90, v182
	ds_read_b128 v[90:93], v110
	ds_read_b128 v[94:97], v110 offset:4096
	ds_read_b128 v[98:101], v121
	ds_read_b128 v[102:105], v121 offset:4096
	ds_read_b128 v[106:109], v110 offset:8192
	ds_read_b128 v[110:113], v110 offset:12288
	ds_read_b128 v[114:117], v121 offset:8192
	ds_read_b128 v[146:149], v121 offset:12288
	v_cndmask_b32_e64 v118, 0, -1.0, vcc
	v_cmp_ge_i32_e32 vcc, s20, v0
	s_nop 1
	v_cndmask_b32_e32 v118, 1.0, v118, vcc
	v_pk_mul_f32 v[162:163], v[132:133], v[118:119] op_sel_hi:[1,0]
	s_nop 0
	v_fma_f32 v118, v119, v163, v162
	v_sub_f32_e32 v172, v118, v135
	v_fma_f32 v118, v120, v163, v162
	v_sub_f32_e32 v194, v118, v134
	v_mul_f32_e32 v120, 0, v163
	v_mov_b32_e32 v121, v163
	v_pk_add_f32 v[118:119], v[120:121], v[172:173] op_sel_hi:[1,0]
	v_pk_add_f32 v[150:151], v[120:121], v[194:195] op_sel_hi:[1,0]
	v_pk_fma_f32 v[120:121], v[162:163], s[30:31], v[172:173] op_sel:[1,0,0] op_sel_hi:[1,1,0]
	v_pk_fma_f32 v[152:153], v[162:163], s[30:31], v[194:195] op_sel:[1,0,0] op_sel_hi:[1,1,0]
	v_pk_fma_f32 v[156:157], v[162:163], s[96:97], v[172:173] op_sel:[1,0,0] op_sel_hi:[1,1,0]
	v_pk_fma_f32 v[154:155], v[162:163], s[26:27], v[172:173] op_sel:[1,0,0] op_sel_hi:[1,1,0]
	v_pk_fma_f32 v[160:161], v[162:163], s[96:97], v[194:195] op_sel:[1,0,0] op_sel_hi:[1,1,0]
	v_pk_fma_f32 v[158:159], v[162:163], s[26:27], v[194:195] op_sel:[1,0,0] op_sel_hi:[1,1,0]
	v_pk_fma_f32 v[170:171], v[162:163], s[88:89], v[172:173] op_sel:[1,0,0] op_sel_hi:[1,1,0]
	v_pk_fma_f32 v[168:169], v[162:163], s[98:99], v[172:173] op_sel:[1,0,0] op_sel_hi:[1,1,0]
	v_pk_fma_f32 v[188:189], v[162:163], s[88:89], v[194:195] op_sel:[1,0,0] op_sel_hi:[1,1,0]
	v_pk_fma_f32 v[186:187], v[162:163], s[98:99], v[194:195] op_sel:[1,0,0] op_sel_hi:[1,1,0]
	v_pk_fma_f32 v[192:193], v[162:163], s[82:83], v[172:173] op_sel:[1,0,0] op_sel_hi:[1,1,0]
	v_pk_fma_f32 v[190:191], v[162:163], s[0:1], v[172:173] op_sel:[1,0,0] op_sel_hi:[1,1,0]
	v_pk_fma_f32 v[196:197], v[162:163], s[82:83], v[194:195] op_sel:[1,0,0] op_sel_hi:[1,1,0]
	v_pk_fma_f32 v[194:195], v[162:163], s[0:1], v[194:195] op_sel:[1,0,0] op_sel_hi:[1,1,0]
	s_waitcnt lgkmcnt(0)
	s_setprio 2
	v_mfma_f32_16x16x32_bf16 v[118:121], v[90:93], v[6:9], v[118:121]
	v_mfma_f32_16x16x32_bf16 v[150:153], v[90:93], v[14:17], v[150:153]
	v_mfma_f32_16x16x32_bf16 v[154:157], v[94:97], v[6:9], v[154:157]
	v_mfma_f32_16x16x32_bf16 v[94:97], v[94:97], v[14:17], v[158:161]
	v_mfma_f32_16x16x32_bf16 v[158:161], v[106:109], v[6:9], v[168:171]
	v_mfma_f32_16x16x32_bf16 v[168:171], v[106:109], v[14:17], v[186:189]
	v_mfma_f32_16x16x32_bf16 v[186:189], v[110:113], v[6:9], v[190:193]
	v_mfma_f32_16x16x32_bf16 v[190:193], v[110:113], v[14:17], v[194:197]
	v_mfma_f32_16x16x32_bf16 v[90:93], v[98:101], v[10:13], v[118:121]
	v_mfma_f32_16x16x32_bf16 v[110:113], v[98:101], v[18:21], v[150:153]
	v_mfma_f32_16x16x32_bf16 v[118:121], v[102:105], v[10:13], v[154:157]
	v_mfma_f32_16x16x32_bf16 v[106:109], v[102:105], v[18:21], v[94:97]
	v_mfma_f32_16x16x32_bf16 v[98:101], v[114:117], v[10:13], v[158:161]
	v_mfma_f32_16x16x32_bf16 v[102:105], v[114:117], v[18:21], v[168:171]
	v_mfma_f32_16x16x32_bf16 v[114:117], v[146:149], v[10:13], v[186:189]
	v_mfma_f32_16x16x32_bf16 v[94:97], v[146:149], v[18:21], v[190:193]
	s_setprio 0
	v_cmp_ne_u32_e32 vcc, s20, v0
	s_and_saveexec_b64 s[2:3], vcc
	s_xor_b64 s[2:3], exec, s[2:3]
	s_cbranch_execz .LBB0_213
	s_cmp_lg_u32 s20, 1
	s_cbranch_scc1 .LBB0_213
	v_mov_b32_e32 v93, 0xf149f2ca
	v_mov_b32_e32 v92, v93
	v_mov_b32_e32 v91, v93
	v_mov_b32_e32 v90, v93
	v_mov_b32_e32 v113, v93
	v_mov_b32_e32 v112, v93
	v_mov_b32_e32 v111, v93
	v_mov_b32_e32 v110, v93
	v_mov_b32_e32 v121, v93
	v_mov_b32_e32 v120, v93
	v_mov_b32_e32 v119, v93
	v_mov_b32_e32 v118, v93
	v_mov_b32_e32 v109, v93
	v_mov_b32_e32 v108, v93
	v_mov_b32_e32 v107, v93
	v_mov_b32_e32 v106, v93
	v_mov_b32_e32 v101, v93
	v_mov_b32_e32 v100, v93
	v_mov_b32_e32 v99, v93
	v_mov_b32_e32 v98, v93
	v_mov_b32_e32 v105, v93
	v_mov_b32_e32 v104, v93
	v_mov_b32_e32 v103, v93
	v_mov_b32_e32 v102, v93
